# plus: resnorm row loop vmcnt waits counted against in-flight loads and stores (no full drain every 4 rows)
# speedup vs baseline: 1.0267x; 1.0026x over previous
.LBB0_615:
	s_waitcnt vmcnt(18)
	v_lshlrev_b32_e32 v80, 16, v36
	v_and_b32_e32 v81, 0xffff0000, v36
	v_pk_mul_f32 v[82:83], v[80:81], v[80:81]
	v_lshlrev_b32_e32 v84, 16, v37
	v_and_b32_e32 v85, 0xffff0000, v37
	v_pk_mul_f32 v[86:87], v[84:85], v[84:85]
	v_add_f32_e32 v82, v82, v83
	v_lshlrev_b32_e32 v88, 16, v38
	v_and_b32_e32 v89, 0xffff0000, v38
	v_add_f32_e32 v82, v86, v82
	v_pk_mul_f32 v[90:91], v[88:89], v[88:89]
	v_add_f32_e32 v82, v87, v82
	v_lshlrev_b32_e32 v172, 16, v39
	v_and_b32_e32 v173, 0xffff0000, v39
	v_add_f32_e32 v82, v90, v82
	v_pk_mul_f32 v[92:93], v[172:173], v[172:173]
	v_add_f32_e32 v82, v91, v82
	s_waitcnt vmcnt(16)
	v_lshlrev_b32_e32 v174, 16, v44
	v_and_b32_e32 v175, 0xffff0000, v44
	v_add_f32_e32 v82, v92, v82
	v_pk_mul_f32 v[94:95], v[174:175], v[174:175]
	v_add_f32_e32 v82, v93, v82
	v_lshlrev_b32_e32 v196, 16, v45
	v_and_b32_e32 v197, 0xffff0000, v45
	v_add_f32_e32 v82, v94, v82
	v_pk_mul_f32 v[170:171], v[196:197], v[196:197]
	v_add_f32_e32 v82, v95, v82
	v_lshlrev_b32_e32 v198, 16, v46
	v_and_b32_e32 v199, 0xffff0000, v46
	v_add_f32_e32 v82, v170, v82
	v_pk_mul_f32 v[200:201], v[198:199], v[198:199]
	v_add_f32_e32 v82, v171, v82
	v_lshlrev_b32_e32 v202, 16, v47
	v_and_b32_e32 v203, 0xffff0000, v47
	v_add_f32_e32 v82, v200, v82
	v_pk_mul_f32 v[204:205], v[202:203], v[202:203]
	v_add_f32_e32 v82, v201, v82
	v_add_f32_e32 v82, v204, v82
	v_add_f32_e32 v82, v205, v82
	ds_bpermute_b32 v83, v188, v82
	v_cvt_f32_f16_sdwa v87, v33 dst_sel:DWORD dst_unused:UNUSED_PAD src0_sel:WORD_1
	v_cvt_f32_f16_sdwa v91, v34 dst_sel:DWORD dst_unused:UNUSED_PAD src0_sel:WORD_1
	v_cvt_f32_f16_sdwa v201, v35 dst_sel:DWORD dst_unused:UNUSED_PAD src0_sel:WORD_1
	v_cvt_f32_f16_e32 v200, v35
	s_waitcnt lgkmcnt(0)
	v_add_f32_e32 v82, v82, v83
	ds_bpermute_b32 v83, v189, v82
	v_cvt_f32_f16_sdwa v205, v40 dst_sel:DWORD dst_unused:UNUSED_PAD src0_sel:WORD_1
	v_cvt_f32_f16_e32 v204, v40
	v_cvt_f32_f16_sdwa v207, v41 dst_sel:DWORD dst_unused:UNUSED_PAD src0_sel:WORD_1
	v_cvt_f32_f16_e32 v206, v41
	s_waitcnt lgkmcnt(0)
	v_add_f32_e32 v82, v82, v83
	ds_bpermute_b32 v86, v190, v82
	v_cvt_f32_f16_sdwa v83, v32 dst_sel:DWORD dst_unused:UNUSED_PAD src0_sel:WORD_1
	v_cvt_f32_f16_sdwa v209, v42 dst_sel:DWORD dst_unused:UNUSED_PAD src0_sel:WORD_1
	v_cvt_f32_f16_e32 v208, v42
	v_cvt_f32_f16_sdwa v211, v43 dst_sel:DWORD dst_unused:UNUSED_PAD src0_sel:WORD_1
	s_waitcnt lgkmcnt(0)
	v_add_f32_e32 v90, v82, v86
	ds_bpermute_b32 v92, v191, v90
	v_cvt_f32_f16_e32 v82, v32
	v_cvt_f32_f16_e32 v86, v33
	v_cvt_f32_f16_e32 v210, v43
	v_add_u32_e32 v170, 18, v195
	s_waitcnt lgkmcnt(0)
	v_add_f32_e32 v92, v90, v92
	ds_bpermute_b32 v93, v192, v92
	v_cvt_f32_f16_e32 v90, v34
	v_ashrrev_i32_e32 v171, 31, v170
	s_mov_b64 s[0:1], -1
	s_waitcnt lgkmcnt(0)
	v_add_f32_e32 v92, v92, v93
	ds_bpermute_b32 v93, v193, v92
	s_waitcnt lgkmcnt(0)
	v_add_f32_e32 v92, v92, v93
	v_fmamk_f32 v92, v92, 0x3a800000, v178
	v_mul_f32_e32 v93, 0x4b800000, v92
	v_cmp_gt_f32_e32 vcc, s62, v92
	s_nop 1
	v_cndmask_b32_e32 v92, v92, v93, vcc
	v_rsq_f32_e32 v92, v92
	s_nop 0
	v_mul_f32_e32 v93, 0x45800000, v92
	v_cndmask_b32_e32 v148, v92, v93, vcc
	v_pk_mul_f32 v[80:81], v[148:149], v[80:81] op_sel_hi:[0,1]
	v_pk_fma_f32 v[92:93], v[158:159], v[80:81], v[82:83]
	v_pk_mul_f32 v[80:81], v[148:149], v[84:85] op_sel_hi:[0,1]
	v_pk_fma_f32 v[94:95], v[142:143], v[80:81], v[86:87]
	v_pk_mul_f32 v[80:81], v[148:149], v[88:89] op_sel_hi:[0,1]
	v_pk_fma_f32 v[88:89], v[140:141], v[80:81], v[90:91]
	v_pk_mul_f32 v[80:81], v[148:149], v[172:173] op_sel_hi:[0,1]
	v_pk_fma_f32 v[90:91], v[138:139], v[80:81], v[200:201]
	v_pk_mul_f32 v[80:81], v[148:149], v[174:175] op_sel_hi:[0,1]
	v_pk_fma_f32 v[84:85], v[136:137], v[80:81], v[204:205]
	v_pk_mul_f32 v[80:81], v[148:149], v[196:197] op_sel_hi:[0,1]
	v_pk_fma_f32 v[86:87], v[134:135], v[80:81], v[206:207]
	v_pk_mul_f32 v[80:81], v[148:149], v[198:199] op_sel_hi:[0,1]
	v_pk_mul_f32 v[82:83], v[148:149], v[202:203] op_sel_hi:[0,1]
	v_pk_fma_f32 v[80:81], v[132:133], v[80:81], v[208:209]
	v_pk_fma_f32 v[82:83], v[130:131], v[82:83], v[210:211]
	s_and_b64 vcc, exec, s[38:39]
	v_lshlrev_b64 v[172:173], 11, v[170:171]
	s_cbranch_vccz .LBB0_618
	v_lshl_add_u64 v[174:175], v[100:101], 0, v[172:173]
	v_cvt_pk_f16_f32 v199, v90, v91
	v_cvt_pk_f16_f32 v198, v88, v89
	v_cvt_pk_f16_f32 v197, v94, v95
	v_cvt_pk_f16_f32 v196, v92, v93
	global_store_dwordx4 v[174:175], v[196:199], off nt
	s_nop 1
	v_cvt_pk_f16_f32 v199, v82, v83
	v_cvt_pk_f16_f32 v198, v80, v81
	v_cvt_pk_f16_f32 v197, v86, v87
	v_cvt_pk_f16_f32 v196, v84, v85
	global_store_dwordx4 v[174:175], v[196:199], off offset:1024 nt
	s_cbranch_execz .LBB0_619

.LBB0_626:
	s_waitcnt vmcnt(17)
	v_lshlrev_b32_e32 v80, 16, v52
	v_and_b32_e32 v81, 0xffff0000, v52
	v_pk_mul_f32 v[82:83], v[80:81], v[80:81]
	v_lshlrev_b32_e32 v84, 16, v53
	v_and_b32_e32 v85, 0xffff0000, v53
	v_pk_mul_f32 v[86:87], v[84:85], v[84:85]
	v_add_f32_e32 v82, v82, v83
	v_lshlrev_b32_e32 v88, 16, v54
	v_and_b32_e32 v89, 0xffff0000, v54
	v_add_f32_e32 v82, v86, v82
	v_pk_mul_f32 v[90:91], v[88:89], v[88:89]
	v_add_f32_e32 v82, v87, v82
	v_lshlrev_b32_e32 v172, 16, v55
	v_and_b32_e32 v173, 0xffff0000, v55
	v_add_f32_e32 v82, v90, v82
	v_pk_mul_f32 v[92:93], v[172:173], v[172:173]
	v_add_f32_e32 v82, v91, v82
	s_waitcnt vmcnt(16)
	v_lshlrev_b32_e32 v174, 16, v60
	v_and_b32_e32 v175, 0xffff0000, v60
	v_add_f32_e32 v82, v92, v82
	v_pk_mul_f32 v[94:95], v[174:175], v[174:175]
	v_add_f32_e32 v82, v93, v82
	v_lshlrev_b32_e32 v196, 16, v61
	v_and_b32_e32 v197, 0xffff0000, v61
	v_add_f32_e32 v82, v94, v82
	v_pk_mul_f32 v[170:171], v[196:197], v[196:197]
	v_add_f32_e32 v82, v95, v82
	v_lshlrev_b32_e32 v198, 16, v62
	v_and_b32_e32 v199, 0xffff0000, v62
	v_add_f32_e32 v82, v170, v82
	v_pk_mul_f32 v[200:201], v[198:199], v[198:199]
	v_add_f32_e32 v82, v171, v82
	v_lshlrev_b32_e32 v202, 16, v63
	v_and_b32_e32 v203, 0xffff0000, v63
	v_add_f32_e32 v82, v200, v82
	v_pk_mul_f32 v[204:205], v[202:203], v[202:203]
	v_add_f32_e32 v82, v201, v82
	v_add_f32_e32 v82, v204, v82
	v_add_f32_e32 v82, v205, v82
	ds_bpermute_b32 v83, v188, v82
	v_cvt_f32_f16_sdwa v87, v49 dst_sel:DWORD dst_unused:UNUSED_PAD src0_sel:WORD_1
	v_cvt_f32_f16_sdwa v91, v50 dst_sel:DWORD dst_unused:UNUSED_PAD src0_sel:WORD_1
	v_cvt_f32_f16_sdwa v201, v51 dst_sel:DWORD dst_unused:UNUSED_PAD src0_sel:WORD_1
	v_cvt_f32_f16_e32 v200, v51
	s_waitcnt lgkmcnt(0)
	v_add_f32_e32 v82, v82, v83
	ds_bpermute_b32 v83, v189, v82
	v_cvt_f32_f16_sdwa v205, v56 dst_sel:DWORD dst_unused:UNUSED_PAD src0_sel:WORD_1
	v_cvt_f32_f16_e32 v204, v56
	v_cvt_f32_f16_sdwa v207, v57 dst_sel:DWORD dst_unused:UNUSED_PAD src0_sel:WORD_1
	v_cvt_f32_f16_e32 v206, v57
	s_waitcnt lgkmcnt(0)
	v_add_f32_e32 v82, v82, v83
	ds_bpermute_b32 v86, v190, v82
	v_cvt_f32_f16_sdwa v83, v48 dst_sel:DWORD dst_unused:UNUSED_PAD src0_sel:WORD_1
	v_cvt_f32_f16_sdwa v209, v58 dst_sel:DWORD dst_unused:UNUSED_PAD src0_sel:WORD_1
	v_cvt_f32_f16_e32 v208, v58
	v_cvt_f32_f16_sdwa v211, v59 dst_sel:DWORD dst_unused:UNUSED_PAD src0_sel:WORD_1
	s_waitcnt lgkmcnt(0)
	v_add_f32_e32 v90, v82, v86
	ds_bpermute_b32 v92, v191, v90
	v_cvt_f32_f16_e32 v82, v48
	v_cvt_f32_f16_e32 v86, v49
	v_cvt_f32_f16_e32 v210, v59
	v_add_u32_e32 v170, 19, v195
	s_waitcnt lgkmcnt(0)
	v_add_f32_e32 v92, v90, v92
	ds_bpermute_b32 v93, v192, v92
	v_cvt_f32_f16_e32 v90, v50
	v_ashrrev_i32_e32 v171, 31, v170
	s_mov_b64 s[0:1], -1
	s_waitcnt lgkmcnt(0)
	v_add_f32_e32 v92, v92, v93
	ds_bpermute_b32 v93, v193, v92
	s_waitcnt lgkmcnt(0)
	v_add_f32_e32 v92, v92, v93
	v_fmamk_f32 v92, v92, 0x3a800000, v178
	v_mul_f32_e32 v93, 0x4b800000, v92
	v_cmp_gt_f32_e32 vcc, s62, v92
	s_nop 1
	v_cndmask_b32_e32 v92, v92, v93, vcc
	v_rsq_f32_e32 v92, v92
	s_nop 0
	v_mul_f32_e32 v93, 0x45800000, v92
	v_cndmask_b32_e32 v148, v92, v93, vcc
	v_pk_mul_f32 v[80:81], v[148:149], v[80:81] op_sel_hi:[0,1]
	v_pk_fma_f32 v[92:93], v[158:159], v[80:81], v[82:83]
	v_pk_mul_f32 v[80:81], v[148:149], v[84:85] op_sel_hi:[0,1]
	v_pk_fma_f32 v[94:95], v[142:143], v[80:81], v[86:87]
	v_pk_mul_f32 v[80:81], v[148:149], v[88:89] op_sel_hi:[0,1]
	v_pk_fma_f32 v[88:89], v[140:141], v[80:81], v[90:91]
	v_pk_mul_f32 v[80:81], v[148:149], v[172:173] op_sel_hi:[0,1]
	v_pk_fma_f32 v[90:91], v[138:139], v[80:81], v[200:201]
	v_pk_mul_f32 v[80:81], v[148:149], v[174:175] op_sel_hi:[0,1]
	v_pk_fma_f32 v[84:85], v[136:137], v[80:81], v[204:205]
	v_pk_mul_f32 v[80:81], v[148:149], v[196:197] op_sel_hi:[0,1]
	v_pk_fma_f32 v[86:87], v[134:135], v[80:81], v[206:207]
	v_pk_mul_f32 v[80:81], v[148:149], v[198:199] op_sel_hi:[0,1]
	v_pk_mul_f32 v[82:83], v[148:149], v[202:203] op_sel_hi:[0,1]
	v_pk_fma_f32 v[80:81], v[132:133], v[80:81], v[208:209]
	v_pk_fma_f32 v[82:83], v[130:131], v[82:83], v[210:211]
	s_and_b64 vcc, exec, s[38:39]
	v_lshlrev_b64 v[172:173], 11, v[170:171]
	s_cbranch_vccz .LBB0_629
	v_lshl_add_u64 v[174:175], v[100:101], 0, v[172:173]
	v_cvt_pk_f16_f32 v199, v90, v91
	v_cvt_pk_f16_f32 v198, v88, v89
	v_cvt_pk_f16_f32 v197, v94, v95
	v_cvt_pk_f16_f32 v196, v92, v93
	global_store_dwordx4 v[174:175], v[196:199], off nt
	s_nop 1
	v_cvt_pk_f16_f32 v199, v82, v83
	v_cvt_pk_f16_f32 v198, v80, v81
	v_cvt_pk_f16_f32 v197, v86, v87
	v_cvt_pk_f16_f32 v196, v84, v85
	global_store_dwordx4 v[174:175], v[196:199], off offset:1024 nt
	s_cbranch_execz .LBB0_630

.LBB0_637:
	s_waitcnt vmcnt(13)
	v_lshlrev_b32_e32 v80, 16, v76
	v_and_b32_e32 v81, 0xffff0000, v76
	v_pk_mul_f32 v[82:83], v[80:81], v[80:81]
	v_lshlrev_b32_e32 v84, 16, v77
	v_and_b32_e32 v85, 0xffff0000, v77
	v_pk_mul_f32 v[76:77], v[84:85], v[84:85]
	v_add_f32_e32 v82, v82, v83
	v_lshlrev_b32_e32 v86, 16, v78
	v_and_b32_e32 v87, 0xffff0000, v78
	v_add_f32_e32 v76, v76, v82
	v_pk_mul_f32 v[88:89], v[86:87], v[86:87]
	v_add_f32_e32 v76, v77, v76
	v_lshlrev_b32_e32 v90, 16, v79
	v_and_b32_e32 v91, 0xffff0000, v79
	v_add_f32_e32 v76, v88, v76
	v_pk_mul_f32 v[78:79], v[90:91], v[90:91]
	v_add_f32_e32 v76, v89, v76
	s_waitcnt vmcnt(12)
	v_lshlrev_b32_e32 v92, 16, v72
	v_and_b32_e32 v93, 0xffff0000, v72
	v_add_f32_e32 v76, v78, v76
	v_pk_mul_f32 v[94:95], v[92:93], v[92:93]
	v_add_f32_e32 v76, v79, v76
	v_lshlrev_b32_e32 v170, 16, v73
	v_and_b32_e32 v171, 0xffff0000, v73
	v_add_f32_e32 v76, v94, v76
	v_pk_mul_f32 v[72:73], v[170:171], v[170:171]
	v_add_f32_e32 v76, v95, v76
	v_lshlrev_b32_e32 v172, 16, v74
	v_and_b32_e32 v173, 0xffff0000, v74
	v_add_f32_e32 v72, v72, v76
	v_pk_mul_f32 v[174:175], v[172:173], v[172:173]
	v_add_f32_e32 v72, v73, v72
	v_lshlrev_b32_e32 v196, 16, v75
	v_and_b32_e32 v197, 0xffff0000, v75
	v_add_f32_e32 v72, v174, v72
	v_pk_mul_f32 v[74:75], v[196:197], v[196:197]
	v_add_f32_e32 v72, v175, v72
	v_add_f32_e32 v72, v74, v72
	v_add_f32_e32 v72, v75, v72
	ds_bpermute_b32 v73, v188, v72
	v_cvt_f32_f16_sdwa v75, v69 dst_sel:DWORD dst_unused:UNUSED_PAD src0_sel:WORD_1
	v_cvt_f32_f16_sdwa v83, v71 dst_sel:DWORD dst_unused:UNUSED_PAD src0_sel:WORD_1
	v_cvt_f32_f16_e32 v82, v71
	v_cvt_f32_f16_sdwa v71, v64 dst_sel:DWORD dst_unused:UNUSED_PAD src0_sel:WORD_1
	s_waitcnt lgkmcnt(0)
	v_add_f32_e32 v72, v72, v73
	ds_bpermute_b32 v73, v189, v72
	v_cvt_f32_f16_sdwa v89, v65 dst_sel:DWORD dst_unused:UNUSED_PAD src0_sel:WORD_1
	v_cvt_f32_f16_e32 v88, v65
	v_cvt_f32_f16_sdwa v65, v66 dst_sel:DWORD dst_unused:UNUSED_PAD src0_sel:WORD_1
	v_cvt_f32_f16_sdwa v95, v67 dst_sel:DWORD dst_unused:UNUSED_PAD src0_sel:WORD_1
	s_waitcnt lgkmcnt(0)
	v_add_f32_e32 v72, v72, v73
	ds_bpermute_b32 v74, v190, v72
	v_cvt_f32_f16_sdwa v73, v68 dst_sel:DWORD dst_unused:UNUSED_PAD src0_sel:WORD_1
	v_cvt_f32_f16_e32 v94, v67
	s_mov_b64 s[0:1], -1
	s_waitcnt lgkmcnt(0)
	v_add_f32_e32 v76, v72, v74
	ds_bpermute_b32 v77, v191, v76
	v_cvt_f32_f16_e32 v72, v68
	v_cvt_f32_f16_e32 v74, v69
	v_cvt_f32_f16_sdwa v69, v70 dst_sel:DWORD dst_unused:UNUSED_PAD src0_sel:WORD_1
	v_cvt_f32_f16_e32 v68, v70
	s_waitcnt lgkmcnt(0)
	v_add_f32_e32 v76, v76, v77
	ds_bpermute_b32 v77, v192, v76
	v_cvt_f32_f16_e32 v70, v64
	s_waitcnt lgkmcnt(0)
	v_add_f32_e32 v76, v76, v77
	ds_bpermute_b32 v77, v193, v76
	s_waitcnt lgkmcnt(0)
	v_add_f32_e32 v64, v76, v77
	v_fmamk_f32 v64, v64, 0x3a800000, v178
	v_mul_f32_e32 v76, 0x4b800000, v64
	v_cmp_gt_f32_e32 vcc, s62, v64
	s_nop 1
	v_cndmask_b32_e32 v64, v64, v76, vcc
	v_rsq_f32_e32 v76, v64
	v_cvt_f32_f16_e32 v64, v66
	v_mul_f32_e32 v66, 0x45800000, v76
	v_cndmask_b32_e32 v66, v76, v66, vcc
	v_pk_mul_f32 v[76:77], v[66:67], v[80:81] op_sel_hi:[0,1]
	v_pk_fma_f32 v[76:77], v[158:159], v[76:77], v[72:73]
	v_pk_mul_f32 v[72:73], v[66:67], v[84:85] op_sel_hi:[0,1]
	v_pk_fma_f32 v[78:79], v[142:143], v[72:73], v[74:75]
	v_pk_mul_f32 v[72:73], v[66:67], v[86:87] op_sel_hi:[0,1]
	v_pk_fma_f32 v[72:73], v[140:141], v[72:73], v[68:69]
	v_pk_mul_f32 v[68:69], v[66:67], v[90:91] op_sel_hi:[0,1]
	v_pk_fma_f32 v[74:75], v[138:139], v[68:69], v[82:83]
	v_pk_mul_f32 v[68:69], v[66:67], v[92:93] op_sel_hi:[0,1]
	v_pk_fma_f32 v[68:69], v[136:137], v[68:69], v[70:71]
	v_pk_mul_f32 v[70:71], v[66:67], v[170:171] op_sel_hi:[0,1]
	v_pk_mul_f32 v[80:81], v[66:67], v[172:173] op_sel_hi:[0,1]
	v_pk_mul_f32 v[66:67], v[66:67], v[196:197] op_sel_hi:[0,1]
	v_pk_fma_f32 v[70:71], v[134:135], v[70:71], v[88:89]
	v_pk_fma_f32 v[64:65], v[132:133], v[80:81], v[64:65]
	v_pk_fma_f32 v[66:67], v[130:131], v[66:67], v[94:95]
	s_and_b64 vcc, exec, s[38:39]
	s_cbranch_vccz .LBB0_640
	v_cvt_pk_f16_f32 v83, v74, v75
	v_cvt_pk_f16_f32 v82, v72, v73
	v_cvt_pk_f16_f32 v81, v78, v79
	v_cvt_pk_f16_f32 v80, v76, v77
	global_store_dwordx4 v[168:169], v[80:83], off nt
	s_nop 1
	v_cvt_pk_f16_f32 v83, v66, v67
	v_cvt_pk_f16_f32 v82, v64, v65
	v_cvt_pk_f16_f32 v81, v70, v71
	v_cvt_pk_f16_f32 v80, v68, v69
	global_store_dwordx4 v[168:169], v[80:83], off offset:1024 nt
	s_cbranch_execz .LBB0_641
